# combined: LN peepholes + windowed interior tiles + windowed second score accumulator takes the -max vector as MFMA C operand directly (8 v_mov_b64 per tile removed)
# baseline (speedup 1.0000x reference)
; #define MFMA32(a, b, c) __builtin_amdgcn_mfma_f32_32x32x16_bf16((a), (b), (c), 0, 0, 0)
; template <int MODE>
; DI void attn_item(const Params& p, int layer, int b, int hq, int qb, u16* lds, const int WAVE_S) {
;     ...
;     f32x16 sc[2];
; #pragma unroll
;     for (int k2 = 0; k2 < 2; ++k2) {
; #pragma unroll
;       for (int ks = 0; ks < 4; ++ks) {
;         const bf16x8 kf = *(const bf16x8*)(Ks + (k2 * 32 + r) * LSTR + ks * 16 + h * 8);
;         sc[k2] = (ks == 0) ? MFMA32(kf, qf[0], negm) : MFMA32(kf, qf[ks], sc[k2]);
;       }
;     }
;     if (MODE == 1) {
;       const float tposf = (float)(q0 + r - (kbase0 + t * 64) - 4 * h);
; #pragma unroll
;       for (int k2 = 0; k2 < 2; ++k2)
; #pragma unroll
;         for (int i = 0; i < 16; ++i) {
;           const float dist = fabsf(tposf - (float)(k2 * 32 + (i & 3) + 8 * (i >> 2)));
;           sc[k2][i] = (dist <= 128.f) ? (sc[k2][i] - slope2 * dist) : -1e30f;
;         }
;     }
;     float mx0 = fmaxf(fmaxf(sc[0][0], sc[0][1]), sc[0][2]), mx1 = fmaxf(fmaxf(sc[1][0], sc[1][1]), sc[1][2]);
; #pragma unroll
;     for (int i = 3; i < 15; i += 2) { mx0 = fmaxf(fmaxf(mx0, sc[0][i]), sc[0][i + 1]); mx1 = fmaxf(fmaxf(mx1, sc[1][i]), sc[1][i + 1]); }
;     float mx = fmaxf(fmaxf(mx0, mx1), fmaxf(sc[0][15], sc[1][15]));
.LBB0_184:
	v_max_i32_e32 v50, s85, v116
	v_add_u32_e32 v50, s96, v50
	v_cmp_gt_i32_e32 vcc, s34, v130
	s_and_saveexec_b64 s[18:19], vcc
	s_lshl_b32 s44, s28, 6
	s_add_i32 s44, s44, s84
	v_sub_u32_e32 v50, s44, v130
	s_or_b64 exec, exec, s[18:19]
	s_movk_i32 s18, 0x81
	v_cmp_gt_i32_e32 vcc, s18, v50
	s_and_saveexec_b64 s[44:45], vcc
	s_cbranch_execz .LBB0_180
	s_and_b32 s18, s97, 0x80
	s_mulk_i32 s18, 0x90
	v_add_u32_e32 v133, s18, v131
	ds_read_b128 v[50:53], v133
	ds_read_b128 v[54:57], v133 offset:32
	ds_read_b128 v[134:137], v133 offset:4608
	v_cvt_f32_i32_e32 v128, v132
	s_waitcnt lgkmcnt(2)
	v_mfma_f32_32x32x16_bf16 v[66:81], v[50:53], v[82:85], v[2:17]
	ds_read_b128 v[50:53], v133 offset:64
	s_waitcnt lgkmcnt(2)
	v_mfma_f32_32x32x16_bf16 v[66:81], v[54:57], v[86:89], v[66:81]
	s_waitcnt lgkmcnt(0)
	v_mfma_f32_32x32x16_bf16 v[66:81], v[50:53], v[90:93], v[66:81]
	ds_read_b128 v[50:53], v133 offset:96
	s_waitcnt lgkmcnt(0)
	v_mfma_f32_32x32x16_bf16 v[66:81], v[50:53], v[94:97], v[66:81]
	v_mfma_f32_32x32x16_bf16 v[50:65], v[134:137], v[82:85], v[2:17]
	ds_read_b128 v[134:137], v133 offset:4640
	s_waitcnt lgkmcnt(0)
	v_mfma_f32_32x32x16_bf16 v[50:65], v[134:137], v[86:89], v[50:65]
	ds_read_b128 v[134:137], v133 offset:4672
	s_waitcnt lgkmcnt(0)
	v_mfma_f32_32x32x16_bf16 v[50:65], v[134:137], v[90:93], v[50:65]
	ds_read_b128 v[134:137], v133 offset:4704
	s_waitcnt lgkmcnt(0)
	v_mfma_f32_32x32x16_bf16 v[50:65], v[134:137], v[94:97], v[50:65]
	s_cmp_gt_i32 s101, 0x80
	s_cbranch_scc1 .Lwin_masked
	s_cmp_lt_i32 s100, 0xffffffbb
	s_cbranch_scc1 .Lwin_masked
	v_add_f32_e32 v136, -1.0, v128
	v_fma_f32 v134, -v120, |v128|, v66
	v_fma_f32 v135, -v121, |v136|, v67
	v_mov_b32_e32 v66, v135
	v_mov_b32_e32 v67, v134
	v_pk_add_f32 v[134:135], v[128:129], s[2:3] op_sel_hi:[0,1]
	v_fma_f32 v136, -v120, |v134|, v68
	v_fma_f32 v137, -v121, |v135|, v69
	v_mov_b32_e32 v68, v137
	v_pk_add_f32 v[134:135], v[128:129], s[38:39] op_sel_hi:[0,1]
	v_mov_b32_e32 v69, v136
	v_fma_f32 v136, -v120, |v134|, v70
	v_fma_f32 v137, -v121, |v135|, v71
	v_mov_b32_e32 v70, v137
	v_pk_add_f32 v[134:135], v[128:129], s[4:5] op_sel_hi:[0,1]
	v_mov_b32_e32 v71, v136
	v_fma_f32 v136, -v120, |v134|, v72
	v_fma_f32 v137, -v121, |v135|, v73
	v_mov_b32_e32 v72, v137
	v_pk_add_f32 v[134:135], v[128:129], s[52:53] op_sel_hi:[0,1]
	v_mov_b32_e32 v73, v136
	v_fma_f32 v136, -v120, |v134|, v74
	v_fma_f32 v137, -v121, |v135|, v75
	v_mov_b32_e32 v74, v137
	v_pk_add_f32 v[134:135], v[128:129], s[26:27] op_sel_hi:[0,1]
	v_mov_b32_e32 v75, v136
	v_fma_f32 v136, -v120, |v134|, v76
	v_fma_f32 v137, -v121, |v135|, v77
	v_mov_b32_e32 v76, v137
	v_pk_add_f32 v[134:135], v[128:129], s[76:77] op_sel_hi:[0,1]
	v_mov_b32_e32 v77, v136
	v_fma_f32 v136, -v120, |v134|, v78
	v_fma_f32 v137, -v121, |v135|, v79
	v_mov_b32_e32 v78, v137
	v_pk_add_f32 v[134:135], v[128:129], s[22:23] op_sel_hi:[0,1]
	v_mov_b32_e32 v79, v136
	v_fma_f32 v136, -v120, |v134|, v80
	v_fma_f32 v137, -v121, |v135|, v81
	v_mov_b32_e32 v80, v137
	v_pk_add_f32 v[134:135], v[128:129], s[10:11] op_sel_hi:[0,1]
	v_mov_b32_e32 v81, v136
	v_fma_f32 v136, -v120, |v134|, v50
	v_fma_f32 v137, -v121, |v135|, v51
	v_mov_b32_e32 v50, v137
	v_pk_add_f32 v[134:135], v[128:129], s[30:31] op_sel_hi:[0,1]
	v_mov_b32_e32 v51, v136
	v_fma_f32 v136, -v120, |v134|, v52
	v_fma_f32 v137, -v121, |v135|, v53
	v_mov_b32_e32 v52, v137
	v_pk_add_f32 v[134:135], v[128:129], s[20:21] op_sel_hi:[0,1]
	v_mov_b32_e32 v53, v136
	v_fma_f32 v136, -v120, |v134|, v54
	v_fma_f32 v137, -v121, |v135|, v55
	v_mov_b32_e32 v54, v137
	v_pk_add_f32 v[134:135], v[128:129], s[6:7] op_sel_hi:[0,1]
	v_mov_b32_e32 v55, v136
	v_fma_f32 v136, -v120, |v134|, v56
	v_fma_f32 v137, -v121, |v135|, v57
	v_mov_b32_e32 v56, v137
	v_pk_add_f32 v[134:135], v[128:129], s[42:43] op_sel_hi:[0,1]
	v_mov_b32_e32 v57, v136
	v_fma_f32 v136, -v120, |v134|, v58
	v_fma_f32 v137, -v121, |v135|, v59
	v_mov_b32_e32 v58, v137
	v_pk_add_f32 v[134:135], v[128:129], s[14:15] op_sel_hi:[0,1]
	v_mov_b32_e32 v59, v136
	v_fma_f32 v136, -v120, |v134|, v60
	v_fma_f32 v137, -v121, |v135|, v61
	v_mov_b32_e32 v60, v137
	v_pk_add_f32 v[134:135], v[128:129], s[82:83] op_sel_hi:[0,1]
	v_mov_b32_e32 v61, v136
	v_fma_f32 v136, -v120, |v134|, v62
	v_fma_f32 v137, -v121, |v135|, v63
	v_mov_b32_e32 v62, v137
	v_pk_add_f32 v[134:135], v[128:129], s[8:9] op_sel_hi:[0,1]
	v_mov_b32_e32 v63, v136
	v_fma_f32 v136, -v120, |v134|, v64
	v_fma_f32 v137, -v121, |v135|, v65
	v_max3_f32 v128, v67, v66, v69
	v_max3_f32 v128, v128, v68, v71
	v_mov_b32_e32 v64, v137
	v_max3_f32 v134, v51, v50, v53
	v_max3_f32 v134, v134, v52, v55
	v_max3_f32 v128, v128, v70, v73
	v_max3_f32 v134, v134, v54, v57
	v_max3_f32 v128, v128, v72, v75
	v_max3_f32 v134, v134, v56, v59
	v_max3_f32 v128, v128, v74, v77
	v_max3_f32 v134, v134, v58, v61
	v_mov_b32_e32 v65, v136
	v_max3_f32 v128, v128, v76, v79
	v_max3_f32 v134, v134, v60, v63
	v_max3_f32 v128, v128, v78, v81
	v_max3_f32 v134, v134, v62, v65
	v_max_f32_e32 v135, v80, v64
	v_max3_f32 v128, v128, v134, v135
	v_mov_b32_e32 v134, v128
	s_nop 1
	v_permlane32_swap_b32_e32 v128, v134
	v_max_f32_e32 v134, v134, v134
	v_max_f32_e32 v128, v128, v128
	v_max_f32_e32 v128, v128, v134
	s_branch .Lwin_join
